# ctx attention tile loop: K/V LDS tile double-buffered (base registers XOR-toggled per tile), one s_barrier per tile instead of two
# speedup vs baseline: 1.0184x; 1.0002x over previous
.LBB0_442:
	ds_read_b128 v[82:85], v77
	ds_read_b128 v[86:89], v77 offset:2048
	ds_read_b128 v[94:97], v78
	ds_read_b128 v[102:105], v78 offset:2048
	s_mov_b32 s2, 0x7060302
	s_waitcnt lgkmcnt(3)
	v_mfma_f32_16x16x32_bf16 v[90:93], v[82:85], v[28:31], 0
	s_cmp_lg_u32 s24, 8
	s_waitcnt lgkmcnt(2)
	v_mfma_f32_16x16x32_bf16 v[98:101], v[86:89], v[28:31], 0
	s_waitcnt lgkmcnt(1)
	v_mfma_f32_16x16x32_bf16 v[90:93], v[94:97], v[32:35], v[90:93]
	s_waitcnt lgkmcnt(0)
	v_mfma_f32_16x16x32_bf16 v[98:101], v[102:105], v[32:35], v[98:101]
	v_mfma_f32_16x16x32_bf16 v[82:85], v[82:85], v[36:39], 0
	s_nop 4
	v_max_f32_e32 v59, v91, v91
	v_max_f32_e32 v61, v90, v90
	v_max_f32_e32 v66, v93, v93
	v_max_f32_e32 v67, v92, v92
	v_max_f32_e32 v106, v101, v101
	v_max_f32_e32 v107, v100, v100
	v_max_f32_e32 v59, v61, v59
	v_max_f32_e32 v61, v67, v66
	v_max_f32_e32 v66, v107, v106
	v_max3_f32 v66, v98, v99, v66
	v_max3_f32 v59, v59, v61, v66
	v_mov_b32_e32 v66, v59
	v_mov_b32_e32 v61, v59
	s_nop 1
	v_permlane16_swap_b32_e32 v66, v61
	v_max_f32_e32 v61, v66, v61
	v_mfma_f32_16x16x32_bf16 v[86:89], v[86:89], v[36:39], 0
	v_add_u32_e32 v67, 0x1000, v79
	ds_read2_b64 v[106:109], v67 offset1:4
	s_waitcnt lgkmcnt(1)
	v_max_f32_e32 v61, v61, v61
	v_max_f32_e32 v59, v59, v61
	v_mov_b32_e32 v66, v59
	v_mov_b32_e32 v61, v59
	s_nop 1
	v_permlane32_swap_b32_e32 v66, v61
	v_max_f32_e32 v61, v66, v61
	v_mfma_f32_16x16x32_bf16 v[82:85], v[94:97], v[44:47], v[82:85]
	s_waitcnt lgkmcnt(0)
	v_max3_f32 v59, v81, v59, v61
	v_sub_f32_e32 v61, v81, v59
	v_sub_f32_e32 v81, v91, v59
	v_mul_f32_e32 v81, 0x3fb8aa3b, v81
	v_exp_f32_e32 v110, v81
	v_sub_f32_e32 v81, v93, v59
	v_mul_f32_e32 v81, 0x3fb8aa3b, v81
	v_exp_f32_e32 v114, v81
	v_sub_f32_e32 v81, v98, v59
	v_mul_f32_e32 v81, 0x3fb8aa3b, v81
	v_exp_f32_e32 v116, v81
	v_sub_f32_e32 v81, v99, v59
	v_mul_f32_e32 v81, 0x3fb8aa3b, v81
	v_exp_f32_e32 v118, v81
	v_sub_f32_e32 v81, v101, v59
	v_mul_f32_e32 v81, 0x3fb8aa3b, v81
	v_sub_f32_e32 v66, v90, v59
	v_sub_f32_e32 v90, v92, v59
	v_exp_f32_e32 v120, v81
	v_sub_f32_e32 v81, v100, v59
	v_mul_f32_e32 v66, 0x3fb8aa3b, v66
	v_mul_f32_e32 v90, 0x3fb8aa3b, v90
	v_mul_f32_e32 v81, 0x3fb8aa3b, v81
	v_exp_f32_e32 v66, v66
	v_exp_f32_e32 v112, v90
	v_exp_f32_e32 v122, v81
	v_mfma_f32_16x16x32_bf16 v[86:89], v[102:105], v[44:47], v[86:89]
	v_cvt_pk_bf16_f32 v93, v122, v120
	v_cvt_pk_bf16_f32 v92, v116, v118
	v_cvt_pk_bf16_f32 v91, v112, v114
	v_cvt_pk_bf16_f32 v90, v66, v110
	v_xor_b32_e32 v98, 16, v67
	ds_read2_b64 v[98:101], v98 offset0:128 offset1:132
	v_max_f32_e32 v67, v83, v83
	v_max_f32_e32 v81, v82, v82
	v_max_f32_e32 v67, v81, v67
	v_max_f32_e32 v81, v85, v85
	v_max_f32_e32 v102, v84, v84
	v_max_f32_e32 v81, v102, v81
	v_max_f32_e32 v102, v89, v89
	v_max_f32_e32 v103, v88, v88
	v_max_f32_e32 v102, v103, v102
	v_max3_f32 v102, v86, v87, v102
	v_max3_f32 v67, v67, v81, v102
	v_mov_b32_e32 v103, v67
	v_mov_b32_e32 v81, v67
	s_nop 1
	v_permlane16_swap_b32_e32 v103, v81
	v_max_f32_e32 v81, v103, v81
	v_mul_f32_e32 v61, 0x3fb8aa3b, v61
	v_exp_f32_e32 v124, v61
	v_add_u32_e32 v61, 0x1800, v79
	ds_read2_b64 v[94:97], v61 offset0:4 offset1:0
	v_xor_b32_e32 v102, 16, v61
	ds_read2_b64 v[102:105], v102 offset0:132 offset1:128
	s_waitcnt lgkmcnt(2)
	v_max_f32_e32 v61, v81, v81
	v_max_f32_e32 v61, v67, v61
	v_mov_b32_e32 v81, v61
	v_mov_b32_e32 v67, v61
	s_nop 1
	v_permlane32_swap_b32_e32 v81, v67
	v_max_f32_e32 v67, v81, v67
	v_pk_mul_f32 v[42:43], v[42:43], v[124:125] op_sel_hi:[1,0]
	v_pk_mul_f32 v[40:41], v[40:41], v[124:125] op_sel_hi:[1,0]
	v_pk_mul_f32 v[26:27], v[26:27], v[124:125] op_sel_hi:[1,0]
	v_pk_mul_f32 v[24:25], v[24:25], v[124:125] op_sel_hi:[1,0]
	s_waitcnt lgkmcnt(0)
	v_max3_f32 v61, v80, v61, v67
	v_sub_f32_e32 v81, v83, v61
	v_mul_f32_e32 v81, 0x3fb8aa3b, v81
	v_exp_f32_e32 v111, v81
	v_sub_f32_e32 v81, v84, v61
	v_sub_f32_e32 v67, v80, v61
	v_mul_f32_e32 v81, 0x3fb8aa3b, v81
	v_mul_f32_e32 v80, 0x3fb8aa3b, v67
	v_sub_f32_e32 v67, v82, v61
	v_exp_f32_e32 v113, v81
	v_sub_f32_e32 v81, v85, v61
	v_mul_f32_e32 v67, 0x3fb8aa3b, v67
	v_mul_f32_e32 v81, 0x3fb8aa3b, v81
	v_exp_f32_e32 v67, v67
	v_exp_f32_e32 v115, v81
	v_sub_f32_e32 v81, v86, v61
	v_sub_f32_e32 v82, v87, v61
	v_sub_f32_e32 v83, v88, v61
	v_sub_f32_e32 v84, v89, v61
	v_mul_f32_e32 v81, 0x3fb8aa3b, v81
	v_mul_f32_e32 v82, 0x3fb8aa3b, v82
	v_mul_f32_e32 v83, 0x3fb8aa3b, v83
	v_mul_f32_e32 v84, 0x3fb8aa3b, v84
	v_exp_f32_e32 v121, v84
	v_exp_f32_e32 v123, v83
	v_exp_f32_e32 v119, v82
	v_exp_f32_e32 v117, v81
	v_pk_mul_f32 v[22:23], v[22:23], v[124:125] op_sel_hi:[1,0]
	v_pk_mul_f32 v[20:21], v[20:21], v[124:125] op_sel_hi:[1,0]
	v_pk_mul_f32 v[18:19], v[18:19], v[124:125] op_sel_hi:[1,0]
	v_pk_mul_f32 v[16:17], v[16:17], v[124:125] op_sel_hi:[1,0]
	v_exp_f32_e32 v125, v80
	v_cvt_pk_bf16_f32 v80, v67, v111
	v_pk_add_f32 v[66:67], v[66:67], 0 op_sel_hi:[1,0]
	v_pk_add_f32 v[66:67], v[110:111], v[66:67]
	v_pk_add_f32 v[66:67], v[112:113], v[66:67]
	v_pk_add_f32 v[66:67], v[114:115], v[66:67]
	v_cvt_pk_bf16_f32 v83, v123, v121
	v_cvt_pk_bf16_f32 v82, v117, v119
	v_mov_b32_e32 v84, v125
	v_pk_add_f32 v[66:67], v[116:117], v[66:67]
	v_cvt_pk_bf16_f32 v81, v113, v115
	v_pk_mul_f32 v[14:15], v[14:15], v[84:85] op_sel_hi:[1,0]
	v_pk_mul_f32 v[12:13], v[12:13], v[84:85] op_sel_hi:[1,0]
	v_pk_mul_f32 v[10:11], v[10:11], v[84:85] op_sel_hi:[1,0]
	v_pk_mul_f32 v[8:9], v[8:9], v[84:85] op_sel_hi:[1,0]
	v_pk_mul_f32 v[6:7], v[6:7], v[84:85] op_sel_hi:[1,0]
	v_pk_mul_f32 v[4:5], v[4:5], v[84:85] op_sel_hi:[1,0]
	v_pk_mul_f32 v[2:3], v[2:3], v[84:85] op_sel_hi:[1,0]
	v_pk_mul_f32 v[0:1], v[0:1], v[84:85] op_sel_hi:[1,0]
	v_mfma_f32_16x16x32_bf16 v[40:43], v[106:109], v[90:93], v[40:43]
	v_add_f32_e64 v66, v118, v66
	v_add_f32_e64 v67, v119, v67
	v_pk_add_f32 v[66:67], v[122:123], v[66:67]
	v_mfma_f32_16x16x32_bf16 v[24:27], v[98:101], v[90:93], v[24:27]
	v_add_f32_e64 v66, v120, v66
	v_add_f32_e64 v67, v121, v67
	v_pk_fma_f32 v[50:51], v[50:51], v[124:125], v[66:67]
	v_mfma_f32_16x16x32_bf16 v[20:23], v[94:97], v[90:93], v[20:23]
	v_mfma_f32_16x16x32_bf16 v[16:19], v[102:105], v[90:93], v[16:19]
	v_mfma_f32_16x16x32_bf16 v[12:15], v[106:109], v[80:83], v[12:15]
	v_mfma_f32_16x16x32_bf16 v[8:11], v[98:101], v[80:83], v[8:11]
	v_mfma_f32_16x16x32_bf16 v[4:7], v[94:97], v[80:83], v[4:7]
	v_mfma_f32_16x16x32_bf16 v[0:3], v[102:105], v[80:83], v[0:3]
	v_mov_b32_e32 v81, v59
	v_mov_b32_e32 v80, v61
	v_xor_b32_e32 v74, 0x2000, v74
	v_xor_b32_e32 v75, 0x2000, v75
	v_xor_b32_e32 v76, 0x2000, v76
	v_xor_b32_e32 v77, 0x2000, v77
	v_xor_b32_e32 v78, 0x2000, v78
	v_xor_b32_e32 v79, 0x2000, v79
	s_cbranch_scc0 .LBB0_447
.LBB0_443:
	v_mov_b32_e32 v59, v129
	v_lshl_add_u64 v[62:63], v[62:63], 0, v[58:59]
	v_mov_b32_e32 v61, v129
	v_lshl_add_u64 v[82:83], v[64:65], 0, v[128:129]
	v_lshl_add_u64 v[62:63], v[62:63], 0, v[60:61]
	global_load_dwordx4 v[64:67], v[82:83], off offset:16
	s_nop 0
	global_load_dwordx4 v[82:85], v[82:83], off
	s_nop 0
	global_load_dwordx4 v[86:89], v[62:63], off offset:64
	global_load_dwordx4 v[90:93], v[62:63], off
	s_mov_b32 s2, s24
	s_add_i32 s24, s24, 1
	s_cmp_lt_u32 s2, 7
	s_cselect_b32 s2, s24, s2
	s_lshl_b32 s3, s2, 5
	s_add_i32 s25, s3, 0xffffff00
	s_cmp_lt_u32 s2, 8
	s_cselect_b32 s3, s3, s25
	s_cmp_gt_u32 s2, 7
	s_waitcnt vmcnt(0)
	v_cvt_pk_bf16_f32 v63, v92, v93
	v_cvt_pk_bf16_f32 v62, v90, v91
	ds_write_b64 v74, v[62:63]
	v_cvt_pk_bf16_f32 v63, v88, v89
	v_cvt_pk_bf16_f32 v62, v86, v87
	v_cvt_pk_bf16_f32 v59, v82, v64
	ds_write_b64 v75, v[62:63]
	ds_write_b16 v76, v59 offset:4096
	ds_write_b16_d16_hi v76, v59 offset:4352
	v_cvt_pk_bf16_f32 v59, v83, v65
	ds_write_b16 v76, v59 offset:4160
	ds_write_b16_d16_hi v76, v59 offset:4416
	v_cvt_pk_bf16_f32 v59, v84, v66
	ds_write_b16 v76, v59 offset:4224
	ds_write_b16_d16_hi v76, v59 offset:4480
	v_cvt_pk_bf16_f32 v59, v85, v67
	ds_write_b16 v76, v59 offset:4288
	v_add_u32_e32 v66, s3, v73
	s_mov_b64 s[2:3], -1
	ds_write_b16_d16_hi v76, v59 offset:4544
	s_waitcnt lgkmcnt(0)
	s_barrier
	s_cbranch_scc0 .LBB0_445
	v_ashrrev_i32_e32 v67, 31, v66
	v_lshl_add_u64 v[62:63], v[66:67], 0, v[54:55]
	v_lshlrev_b64 v[64:65], 9, v[62:63]
	v_readlane_b32 s68, v253, 56
	v_lshl_or_b32 v64, v52, 2, v64
	v_readlane_b32 s74, v253, 62
	v_readlane_b32 s75, v253, 63
	v_readlane_b32 s76, v254, 0
	v_readlane_b32 s77, v254, 1
	v_readlane_b32 s69, v253, 57
	v_readlane_b32 s70, v253, 58
	v_readlane_b32 s71, v253, 59
	v_readlane_b32 s72, v253, 60
	v_readlane_b32 s73, v253, 61
	v_readlane_b32 s78, v254, 2
	v_readlane_b32 s79, v254, 3
	v_readlane_b32 s80, v254, 4
	v_readlane_b32 s81, v254, 5
	v_readlane_b32 s82, v254, 6
	v_readlane_b32 s83, v254, 7
	v_lshl_add_u64 v[62:63], s[74:75], 0, v[64:65]
	v_lshl_add_u64 v[64:65], s[76:77], 0, v[64:65]
	s_mov_b64 s[2:3], 0
